# retention part B (P4): transposed-V reads as ds_read_b64 pairs (removes the 2-way bank conflict of ds_read2_b64), lgkmcnt waits recounted
# baseline (speedup 1.0000x reference)
; __device__ __forceinline__ unsigned pk2(float lo, float hi) { return f2bf(lo) | (f2bf(hi) << 16); }
; #define MFMA16(a, b, c) __builtin_amdgcn_mfma_f32_16x16x32_bf16(a, b, c, 0, 0, 0)
; __device__ __forceinline__ void ret2_task(const Params& p_, int l, int task, unsigned char* lds) {
;     ...
;       const int e = tid >> 3, d0 = (tid & 7) * 8; u32x4 o;
;       o.x = pk2(f0[0], f0[1]); o.y = pk2(f0[2], f0[3]); o.z = pk2(f1[0], f1[1]); o.w = pk2(f1[2], f1[3]); *(u32x4*)((bf16*)(lds + R_STF) + e * 72 + d0) = o;
;       o.x = pk2(g0[0], g0[1]); o.y = pk2(g0[2], g0[3]); o.z = pk2(g1[0], g1[1]); o.w = pk2(g1[2], g1[3]); *(u32x4*)((bf16*)(lds + R_STB) + e * 72 + d0) = o; }
;     __syncthreads();
;     const bf16* QS = (const bf16*)(lds + R_QS); const bf16* KS = (const bf16*)(lds + R_KS); const bf16* VT = (const bf16*)(lds + R_VT);
;     const bf16* STF = (const bf16*)(lds + R_STF); const bf16* STB = (const bf16*)(lds + R_STB);
;     bf16x8v qf[2];
; #pragma unroll
;     for (int ks = 0; ks < 2; ++ks) qf[ks] = *(const bf16x8v*)(QS + (16 * w + fr) * 72 + 32 * ks + 8 * fq);
;     const int ai = 16 * w + fr;
;     unsigned pp[8][2];
; #pragma unroll
;     for (int jt = 0; jt < 8; ++jt) { f32x4 acc = {0.f, 0.f, 0.f, 0.f};
; #pragma unroll
;         for (int ks = 0; ks < 2; ++ks) { const bf16x8v kf = *(const bf16x8v*)(KS + (16 * jt + fr) * 72 + 32 * ks + 8 * fq); acc = MFMA16(kf, qf[ks], acc); }
;         float sc[4];
; #pragma unroll
;         for (int r = 0; r < 4; ++r) { const int aj = 16 * jt + 4 * fq + r; const float wg = (aj <= ai) ? exp2f(l2f * (float)(ai - aj)) : exp2f(l2b * (float)(aj - ai)); sc[r] = acc[r] * wg; }
;         pp[jt][0] = pk2(sc[0], sc[1]); pp[jt][1] = pk2(sc[2], sc[3]); }
.LBB0_562:
	v_bfe_u32 v2, v4, 16, 1
	v_add3_u32 v2, v4, v2, s14
	v_bfe_u32 v3, v5, 16, 1
	v_lshrrev_b32_e32 v2, 16, v2
	v_add3_u32 v3, v5, v3, s14
	v_and_or_b32 v2, v3, s15, v2
	v_bfe_u32 v3, v6, 16, 1
	v_add3_u32 v3, v6, v3, s14
	v_bfe_u32 v4, v7, 16, 1
	v_lshrrev_b32_e32 v3, 16, v3
	v_add3_u32 v4, v7, v4, s14
	v_and_or_b32 v3, v4, s15, v3
	v_bfe_u32 v4, v8, 16, 1
	v_add3_u32 v4, v8, v4, s14
	v_bfe_u32 v5, v9, 16, 1
	v_lshrrev_b32_e32 v4, 16, v4
	v_add3_u32 v5, v9, v5, s14
	v_and_or_b32 v4, v5, s15, v4
	v_bfe_u32 v5, v10, 16, 1
	v_add3_u32 v5, v10, v5, s14
	v_bfe_u32 v6, v11, 16, 1
	v_lshrrev_b32_e32 v20, 3, v79
	v_and_b32_e32 v21, 56, v72
	v_lshrrev_b32_e32 v5, 16, v5
	v_add3_u32 v6, v11, v6, s14
	s_movk_i32 s39, 0x90
	v_and_or_b32 v5, v6, s15, v5
	v_mul_lo_u32 v6, v20, s39
	v_lshlrev_b32_e32 v7, 1, v21
	v_readlane_b32 s6, v255, 26
	s_add_i32 s24, 0, 0x18000
	v_bfe_u32 v0, v79, 4, 2
	v_add3_u32 v8, s6, v6, v7
	ds_write_b128 v8, v[2:5]
	v_bfe_u32 v2, v16, 16, 1
	v_add3_u32 v2, v16, v2, s14
	v_bfe_u32 v3, v17, 16, 1
	v_lshrrev_b32_e32 v2, 16, v2
	v_add3_u32 v3, v17, v3, s14
	v_and_or_b32 v2, v3, s15, v2
	v_bfe_u32 v3, v18, 16, 1
	v_add3_u32 v3, v18, v3, s14
	v_bfe_u32 v4, v19, 16, 1
	v_lshrrev_b32_e32 v3, 16, v3
	v_add3_u32 v4, v19, v4, s14
	v_and_or_b32 v3, v4, s15, v3
	v_bfe_u32 v4, v12, 16, 1
	v_add3_u32 v4, v12, v4, s14
	v_bfe_u32 v5, v13, 16, 1
	v_lshrrev_b32_e32 v4, 16, v4
	v_add3_u32 v5, v13, v5, s14
	v_and_or_b32 v4, v5, s15, v4
	v_bfe_u32 v5, v14, 16, 1
	v_add3_u32 v5, v14, v5, s14
	v_bfe_u32 v8, v15, 16, 1
	v_lshrrev_b32_e32 v5, 16, v5
	v_add3_u32 v8, v15, v8, s14
	v_and_or_b32 v5, v8, s15, v5
	v_add3_u32 v6, s24, v6, v7
	ds_write_b128 v6, v[2:5]
	v_ashrrev_i32_e32 v2, 2, v79
	v_lshlrev_b32_e32 v72, 4, v0
	v_and_b32_e32 v71, 15, v79
	v_bfi_b32 v70, -16, v2, v79
	v_add_u32_e32 v10, 0, v72
	v_mad_u64_u32 v[2:3], s[12:13], v70, s39, v[10:11]
	v_mad_u32_u24 v38, v71, s39, v10
	s_waitcnt lgkmcnt(0)
	s_barrier
	ds_read_b128 v[6:9], v2
	ds_read_b128 v[2:5], v2 offset:64
	ds_read_b128 v[10:13], v38 offset:18432
	ds_read_b128 v[80:83], v38 offset:34560
	ds_read_b128 v[14:17], v38 offset:18496
	ds_read_b128 v[18:21], v38 offset:20800
	s_waitcnt lgkmcnt(3)
	v_mfma_f32_16x16x32_bf16 v[10:13], v[10:13], v[6:9], 0
	v_lshlrev_b32_e32 v73, 2, v0
	v_cmp_gt_i32_e32 vcc, v73, v70
	v_or_b32_e32 v39, 0x60, v73
	s_waitcnt lgkmcnt(1)
	v_mfma_f32_16x16x32_bf16 v[10:13], v[14:17], v[2:5], v[10:13]
	v_sub_u32_e32 v14, v73, v70
	v_sub_u32_e32 v15, 0, v14
	v_max_i32_e32 v14, v14, v15
	v_cvt_f32_u32_e32 v14, v14
	v_cndmask_b32_e32 v15, v78, v75, vcc
	v_or_b32_e32 v74, 0x70, v73
	v_mfma_f32_16x16x32_bf16 v[80:83], v[80:83], v[6:9], 0
	v_mul_f32_e32 v16, v15, v14
	v_cmp_gt_f32_e32 vcc, s69, v16
	v_lshlrev_b32_e32 v0, 3, v0
	s_add_i32 s10, s10, s66
	v_cndmask_b32_e32 v16, 0, v183, vcc
	v_fmac_f32_e32 v16, v15, v14
	v_exp_f32_e32 v14, v16
	v_cndmask_b32_e32 v15, 0, v184, vcc
	v_cmp_lt_i32_e32 vcc, v73, v70
	s_add_i32 s3, s3, s66
	v_ldexp_f32 v42, v14, v15
	v_or_b32_e32 v14, 1, v73
	v_sub_u32_e32 v15, v14, v70
	v_sub_u32_e32 v14, v70, v14
	v_cndmask_b32_e32 v14, v15, v14, vcc
	v_cvt_f32_i32_e32 v14, v14
	v_cndmask_b32_e32 v15, v75, v78, vcc
	ds_read_b128 v[22:25], v38 offset:23104
	ds_read_b128 v[26:29], v38 offset:25408
	v_mul_f32_e32 v16, v15, v14
	v_cmp_gt_f32_e32 vcc, s69, v16
	ds_read_b128 v[30:33], v38 offset:27712
	ds_read_b128 v[34:37], v38 offset:30016
	v_cndmask_b32_e32 v16, 0, v183, vcc
	v_fmac_f32_e32 v16, v15, v14
	v_exp_f32_e32 v14, v16
	v_cndmask_b32_e32 v15, 0, v184, vcc
	ds_read_b128 v[66:69], v38 offset:32320
	v_ldexp_f32 v44, v14, v15
	v_or_b32_e32 v14, 2, v73
	v_cmp_gt_i32_e32 vcc, v14, v70
	v_sub_u32_e32 v14, v14, v70
	v_sub_u32_e32 v15, 0, v14
	v_max_i32_e32 v14, v14, v15
	v_cvt_f32_u32_e32 v14, v14
	v_cndmask_b32_e32 v15, v78, v75, vcc
	v_mul_f32_e32 v16, v15, v14
	v_cmp_gt_f32_e32 vcc, s69, v16
	s_nop 1
	v_cndmask_b32_e32 v16, 0, v183, vcc
	v_fmac_f32_e32 v16, v15, v14
	v_exp_f32_e32 v14, v16
	v_cndmask_b32_e32 v15, 0, v184, vcc
	v_ldexp_f32 v43, v14, v15
	v_or_b32_e32 v14, 3, v73
	v_cmp_gt_i32_e32 vcc, v14, v70
	v_sub_u32_e32 v14, v14, v70
	v_sub_u32_e32 v15, 0, v14
	v_max_i32_e32 v14, v14, v15
	v_cvt_f32_u32_e32 v14, v14
	v_cndmask_b32_e32 v15, v78, v75, vcc
	v_mul_f32_e32 v16, v15, v14
	v_cmp_gt_f32_e32 vcc, s69, v16
	s_nop 1
	v_cndmask_b32_e32 v16, 0, v183, vcc
	v_fmac_f32_e32 v16, v15, v14
	v_exp_f32_e32 v14, v16
	v_cndmask_b32_e32 v15, 0, v184, vcc
	v_ldexp_f32 v45, v14, v15
	ds_read_b128 v[14:17], v38 offset:20736
	s_waitcnt lgkmcnt(0)
	v_mfma_f32_16x16x32_bf16 v[14:17], v[14:17], v[6:9], 0
	v_mfma_f32_16x16x32_bf16 v[14:17], v[18:21], v[2:5], v[14:17]
	v_or_b32_e32 v18, 16, v73
	v_cmp_gt_i32_e32 vcc, v18, v70
	v_sub_u32_e32 v18, v18, v70
	v_sub_u32_e32 v19, 0, v18
	v_max_i32_e32 v18, v18, v19
	v_cvt_f32_u32_e32 v18, v18
	v_cndmask_b32_e32 v19, v78, v75, vcc
	v_mul_f32_e32 v20, v19, v18
	v_cmp_gt_f32_e32 vcc, s69, v20
	s_nop 1
	v_cndmask_b32_e32 v20, 0, v183, vcc
	v_fmac_f32_e32 v20, v19, v18
	v_exp_f32_e32 v18, v20
	v_cndmask_b32_e32 v19, 0, v184, vcc
	v_ldexp_f32 v46, v18, v19
	v_or_b32_e32 v18, 17, v73
	v_cmp_gt_i32_e32 vcc, v18, v70
	v_sub_u32_e32 v18, v18, v70
	v_sub_u32_e32 v19, 0, v18
	v_max_i32_e32 v18, v18, v19
	v_cvt_f32_u32_e32 v18, v18
	v_cndmask_b32_e32 v19, v78, v75, vcc
	v_mul_f32_e32 v20, v19, v18
	v_cmp_gt_f32_e32 vcc, s69, v20
	s_nop 1
	v_cndmask_b32_e32 v20, 0, v183, vcc
	v_fmac_f32_e32 v20, v19, v18
	v_exp_f32_e32 v18, v20
	v_cndmask_b32_e32 v19, 0, v184, vcc
	v_ldexp_f32 v48, v18, v19
	v_or_b32_e32 v18, 18, v73
	v_cmp_gt_i32_e32 vcc, v18, v70
	v_sub_u32_e32 v18, v18, v70
	v_sub_u32_e32 v19, 0, v18
	v_max_i32_e32 v18, v18, v19
	v_cvt_f32_u32_e32 v18, v18
	v_cndmask_b32_e32 v19, v78, v75, vcc
	v_mul_f32_e32 v20, v19, v18
	v_cmp_gt_f32_e32 vcc, s69, v20
	s_nop 1
	v_cndmask_b32_e32 v20, 0, v183, vcc
	v_fmac_f32_e32 v20, v19, v18
	v_exp_f32_e32 v18, v20
	v_cndmask_b32_e32 v19, 0, v184, vcc
	v_ldexp_f32 v47, v18, v19
	v_or_b32_e32 v18, 19, v73
	v_cmp_gt_i32_e32 vcc, v18, v70
	v_sub_u32_e32 v18, v18, v70
	v_sub_u32_e32 v19, 0, v18
	v_max_i32_e32 v18, v18, v19
	v_cvt_f32_u32_e32 v18, v18
	v_cndmask_b32_e32 v19, v78, v75, vcc
	v_mul_f32_e32 v20, v19, v18
	v_cmp_gt_f32_e32 vcc, s69, v20
	s_nop 1
	v_cndmask_b32_e32 v20, 0, v183, vcc
	v_fmac_f32_e32 v20, v19, v18
	v_exp_f32_e32 v18, v20
	v_cndmask_b32_e32 v19, 0, v184, vcc
	v_ldexp_f32 v49, v18, v19
	ds_read_b128 v[18:21], v38 offset:23040
	s_waitcnt lgkmcnt(0)
; __device__ __forceinline__ unsigned pk2(float lo, float hi) { return f2bf(lo) | (f2bf(hi) << 16); }
; #define MFMA16(a, b, c) __builtin_amdgcn_mfma_f32_16x16x32_bf16(a, b, c, 0, 0, 0)
; __device__ __forceinline__ void ret2_task(const Params& p_, int l, int task, unsigned char* lds) {
;     ...
;     for (int jt = 0; jt < 8; ++jt) { f32x4 acc = {0.f, 0.f, 0.f, 0.f};
; #pragma unroll
;         for (int ks = 0; ks < 2; ++ks) { const bf16x8v kf = *(const bf16x8v*)(KS + (16 * jt + fr) * 72 + 32 * ks + 8 * fq); acc = MFMA16(kf, qf[ks], acc); }
;         float sc[4];
; #pragma unroll
;         for (int r = 0; r < 4; ++r) { const int aj = 16 * jt + 4 * fq + r; const float wg = (aj <= ai) ? exp2f(l2f * (float)(ai - aj)) : exp2f(l2b * (float)(aj - ai)); sc[r] = acc[r] * wg; }
;         pp[jt][0] = pk2(sc[0], sc[1]); pp[jt][1] = pk2(sc[2], sc[3]); }
	v_mfma_f32_16x16x32_bf16 v[18:21], v[18:21], v[6:9], 0
	v_mfma_f32_16x16x32_bf16 v[18:21], v[22:25], v[2:5], v[18:21]
	v_or_b32_e32 v22, 32, v73
	v_cmp_gt_i32_e32 vcc, v22, v70
	v_sub_u32_e32 v22, v22, v70
	v_sub_u32_e32 v23, 0, v22
	v_max_i32_e32 v22, v22, v23
	v_cvt_f32_u32_e32 v22, v22
	v_cndmask_b32_e32 v23, v78, v75, vcc
	v_mul_f32_e32 v24, v23, v22
	v_cmp_gt_f32_e32 vcc, s69, v24
	s_nop 1
	v_cndmask_b32_e32 v24, 0, v183, vcc
	v_fmac_f32_e32 v24, v23, v22
	v_exp_f32_e32 v22, v24
	v_cndmask_b32_e32 v23, 0, v184, vcc
	v_ldexp_f32 v50, v22, v23
	v_or_b32_e32 v22, 33, v73
	v_cmp_gt_i32_e32 vcc, v22, v70
	v_sub_u32_e32 v22, v22, v70
	v_sub_u32_e32 v23, 0, v22
	v_max_i32_e32 v22, v22, v23
	v_cvt_f32_u32_e32 v22, v22
	v_cndmask_b32_e32 v23, v78, v75, vcc
	v_mul_f32_e32 v24, v23, v22
	v_cmp_gt_f32_e32 vcc, s69, v24
	s_nop 1
	v_cndmask_b32_e32 v24, 0, v183, vcc
	v_fmac_f32_e32 v24, v23, v22
	v_exp_f32_e32 v22, v24
	v_cndmask_b32_e32 v23, 0, v184, vcc
	v_ldexp_f32 v52, v22, v23
	v_or_b32_e32 v22, 34, v73
	v_cmp_gt_i32_e32 vcc, v22, v70
	v_sub_u32_e32 v22, v22, v70
	v_sub_u32_e32 v23, 0, v22
	v_max_i32_e32 v22, v22, v23
	v_cvt_f32_u32_e32 v22, v22
	v_cndmask_b32_e32 v23, v78, v75, vcc
	v_mul_f32_e32 v24, v23, v22
	v_cmp_gt_f32_e32 vcc, s69, v24
	s_nop 1
	v_cndmask_b32_e32 v24, 0, v183, vcc
	v_fmac_f32_e32 v24, v23, v22
	v_exp_f32_e32 v22, v24
	v_cndmask_b32_e32 v23, 0, v184, vcc
	v_ldexp_f32 v51, v22, v23
	v_or_b32_e32 v22, 35, v73
	v_cmp_gt_i32_e32 vcc, v22, v70
	v_sub_u32_e32 v22, v22, v70
	v_sub_u32_e32 v23, 0, v22
	v_max_i32_e32 v22, v22, v23
	v_cvt_f32_u32_e32 v22, v22
	v_cndmask_b32_e32 v23, v78, v75, vcc
	v_mul_f32_e32 v24, v23, v22
	v_cmp_gt_f32_e32 vcc, s69, v24
	s_nop 1
	v_cndmask_b32_e32 v24, 0, v183, vcc
	v_fmac_f32_e32 v24, v23, v22
	v_exp_f32_e32 v22, v24
	v_cndmask_b32_e32 v23, 0, v184, vcc
	v_ldexp_f32 v53, v22, v23
	ds_read_b128 v[22:25], v38 offset:25344
	s_waitcnt lgkmcnt(0)
	v_mfma_f32_16x16x32_bf16 v[22:25], v[22:25], v[6:9], 0
	v_mfma_f32_16x16x32_bf16 v[22:25], v[26:29], v[2:5], v[22:25]
	v_or_b32_e32 v26, 48, v73
	v_cmp_gt_i32_e32 vcc, v26, v70
	v_sub_u32_e32 v26, v26, v70
	v_sub_u32_e32 v27, 0, v26
	v_max_i32_e32 v26, v26, v27
	v_cvt_f32_u32_e32 v26, v26
	v_cndmask_b32_e32 v27, v78, v75, vcc
	v_mul_f32_e32 v28, v27, v26
	v_cmp_gt_f32_e32 vcc, s69, v28
	s_nop 1
	v_cndmask_b32_e32 v28, 0, v183, vcc
	v_fmac_f32_e32 v28, v27, v26
	v_exp_f32_e32 v26, v28
	v_cndmask_b32_e32 v27, 0, v184, vcc
	v_ldexp_f32 v54, v26, v27
	v_or_b32_e32 v26, 49, v73
	v_cmp_gt_i32_e32 vcc, v26, v70
	v_sub_u32_e32 v26, v26, v70
	v_sub_u32_e32 v27, 0, v26
	v_max_i32_e32 v26, v26, v27
	v_cvt_f32_u32_e32 v26, v26
	v_cndmask_b32_e32 v27, v78, v75, vcc
	v_mul_f32_e32 v28, v27, v26
	v_cmp_gt_f32_e32 vcc, s69, v28
	s_nop 1
	v_cndmask_b32_e32 v28, 0, v183, vcc
	v_fmac_f32_e32 v28, v27, v26
	v_exp_f32_e32 v26, v28
	v_cndmask_b32_e32 v27, 0, v184, vcc
	v_ldexp_f32 v56, v26, v27
	v_or_b32_e32 v26, 50, v73
	v_cmp_gt_i32_e32 vcc, v26, v70
	v_sub_u32_e32 v26, v26, v70
	v_sub_u32_e32 v27, 0, v26
	v_max_i32_e32 v26, v26, v27
	v_cvt_f32_u32_e32 v26, v26
	v_cndmask_b32_e32 v27, v78, v75, vcc
	v_mul_f32_e32 v28, v27, v26
	v_cmp_gt_f32_e32 vcc, s69, v28
	s_nop 1
	v_cndmask_b32_e32 v28, 0, v183, vcc
	v_fmac_f32_e32 v28, v27, v26
	v_exp_f32_e32 v26, v28
	v_cndmask_b32_e32 v27, 0, v184, vcc
	v_ldexp_f32 v55, v26, v27
	v_or_b32_e32 v26, 51, v73
	v_cmp_gt_i32_e32 vcc, v26, v70
	v_sub_u32_e32 v26, v26, v70
	v_sub_u32_e32 v27, 0, v26
	v_max_i32_e32 v26, v26, v27
	v_cvt_f32_u32_e32 v26, v26
	v_cndmask_b32_e32 v27, v78, v75, vcc
	v_mul_f32_e32 v28, v27, v26
	v_cmp_gt_f32_e32 vcc, s69, v28
	s_nop 1
	v_cndmask_b32_e32 v28, 0, v183, vcc
	v_fmac_f32_e32 v28, v27, v26
	v_exp_f32_e32 v26, v28
	v_cndmask_b32_e32 v27, 0, v184, vcc
	v_ldexp_f32 v57, v26, v27
	ds_read_b128 v[26:29], v38 offset:27648
	s_waitcnt lgkmcnt(0)
	v_mfma_f32_16x16x32_bf16 v[26:29], v[26:29], v[6:9], 0
	v_mfma_f32_16x16x32_bf16 v[26:29], v[30:33], v[2:5], v[26:29]
	v_or_b32_e32 v30, 64, v73
	v_cmp_gt_i32_e32 vcc, v30, v70
	v_sub_u32_e32 v30, v30, v70
	v_sub_u32_e32 v31, 0, v30
	v_max_i32_e32 v30, v30, v31
	v_cvt_f32_u32_e32 v30, v30
	v_cndmask_b32_e32 v31, v78, v75, vcc
	v_mul_f32_e32 v32, v31, v30
	v_cmp_gt_f32_e32 vcc, s69, v32
	s_nop 1
	v_cndmask_b32_e32 v32, 0, v183, vcc
	v_fmac_f32_e32 v32, v31, v30
	v_exp_f32_e32 v30, v32
	v_cndmask_b32_e32 v31, 0, v184, vcc
	v_ldexp_f32 v58, v30, v31
	v_or_b32_e32 v30, 0x41, v73
	v_cmp_gt_i32_e32 vcc, v30, v70
	v_sub_u32_e32 v30, v30, v70
	v_sub_u32_e32 v31, 0, v30
	v_max_i32_e32 v30, v30, v31
	v_cvt_f32_u32_e32 v30, v30
	v_cndmask_b32_e32 v31, v78, v75, vcc
	v_mul_f32_e32 v32, v31, v30
	v_cmp_gt_f32_e32 vcc, s69, v32
	s_nop 1
	v_cndmask_b32_e32 v32, 0, v183, vcc
	v_fmac_f32_e32 v32, v31, v30
	v_exp_f32_e32 v30, v32
	v_cndmask_b32_e32 v31, 0, v184, vcc
	v_ldexp_f32 v60, v30, v31
	v_or_b32_e32 v30, 0x42, v73
	v_cmp_gt_i32_e32 vcc, v30, v70
	v_sub_u32_e32 v30, v30, v70
	v_sub_u32_e32 v31, 0, v30
	v_max_i32_e32 v30, v30, v31
	v_cvt_f32_u32_e32 v30, v30
	v_cndmask_b32_e32 v31, v78, v75, vcc
	v_mul_f32_e32 v32, v31, v30
	v_cmp_gt_f32_e32 vcc, s69, v32
	s_nop 1
	v_cndmask_b32_e32 v32, 0, v183, vcc
	v_fmac_f32_e32 v32, v31, v30
	v_exp_f32_e32 v30, v32
	v_cndmask_b32_e32 v31, 0, v184, vcc
	v_ldexp_f32 v59, v30, v31
	v_or_b32_e32 v30, 0x43, v73
	v_cmp_gt_i32_e32 vcc, v30, v70
	v_sub_u32_e32 v30, v30, v70
	v_sub_u32_e32 v31, 0, v30
	v_max_i32_e32 v30, v30, v31
	v_cvt_f32_u32_e32 v30, v30
	v_cndmask_b32_e32 v31, v78, v75, vcc
	v_mul_f32_e32 v32, v31, v30
	v_cmp_gt_f32_e32 vcc, s69, v32
	s_nop 1
	v_cndmask_b32_e32 v32, 0, v183, vcc
	v_fmac_f32_e32 v32, v31, v30
	v_exp_f32_e32 v30, v32
	v_cndmask_b32_e32 v31, 0, v184, vcc
	v_ldexp_f32 v61, v30, v31
	ds_read_b128 v[30:33], v38 offset:29952
	s_waitcnt lgkmcnt(0)
; __device__ __forceinline__ unsigned pk2(float lo, float hi) { return f2bf(lo) | (f2bf(hi) << 16); }
; #define MFMA16(a, b, c) __builtin_amdgcn_mfma_f32_16x16x32_bf16(a, b, c, 0, 0, 0)
; __device__ __forceinline__ void ret2_task(const Params& p_, int l, int task, unsigned char* lds) {
;     ...
;     for (int jt = 0; jt < 8; ++jt) { f32x4 acc = {0.f, 0.f, 0.f, 0.f};
; #pragma unroll
;         for (int ks = 0; ks < 2; ++ks) { const bf16x8v kf = *(const bf16x8v*)(KS + (16 * jt + fr) * 72 + 32 * ks + 8 * fq); acc = MFMA16(kf, qf[ks], acc); }
;         float sc[4];
; #pragma unroll
;         for (int r = 0; r < 4; ++r) { const int aj = 16 * jt + 4 * fq + r; const float wg = (aj <= ai) ? exp2f(l2f * (float)(ai - aj)) : exp2f(l2b * (float)(aj - ai)); sc[r] = acc[r] * wg; }
;         pp[jt][0] = pk2(sc[0], sc[1]); pp[jt][1] = pk2(sc[2], sc[3]); }
	v_mfma_f32_16x16x32_bf16 v[30:33], v[30:33], v[6:9], 0
	v_mfma_f32_16x16x32_bf16 v[30:33], v[34:37], v[2:5], v[30:33]
	v_or_b32_e32 v34, 0x50, v73
	v_cmp_gt_i32_e32 vcc, v34, v70
	v_sub_u32_e32 v34, v34, v70
	v_sub_u32_e32 v35, 0, v34
	v_max_i32_e32 v34, v34, v35
	v_cvt_f32_u32_e32 v34, v34
	v_cndmask_b32_e32 v35, v78, v75, vcc
	v_mul_f32_e32 v36, v35, v34
	v_cmp_gt_f32_e32 vcc, s69, v36
	s_nop 1
	v_cndmask_b32_e32 v36, 0, v183, vcc
	v_fmac_f32_e32 v36, v35, v34
	v_exp_f32_e32 v34, v36
	v_cndmask_b32_e32 v35, 0, v184, vcc
	v_ldexp_f32 v62, v34, v35
	v_or_b32_e32 v34, 0x51, v73
	v_cmp_gt_i32_e32 vcc, v34, v70
	v_sub_u32_e32 v34, v34, v70
	v_sub_u32_e32 v35, 0, v34
	v_max_i32_e32 v34, v34, v35
	v_cvt_f32_u32_e32 v34, v34
	v_cndmask_b32_e32 v35, v78, v75, vcc
	v_mul_f32_e32 v36, v35, v34
	v_cmp_gt_f32_e32 vcc, s69, v36
	s_nop 1
	v_cndmask_b32_e32 v36, 0, v183, vcc
	v_fmac_f32_e32 v36, v35, v34
	v_exp_f32_e32 v34, v36
	v_cndmask_b32_e32 v35, 0, v184, vcc
	v_ldexp_f32 v64, v34, v35
	v_or_b32_e32 v34, 0x52, v73
	v_cmp_gt_i32_e32 vcc, v34, v70
	v_sub_u32_e32 v34, v34, v70
	v_sub_u32_e32 v35, 0, v34
	v_max_i32_e32 v34, v34, v35
	v_cvt_f32_u32_e32 v34, v34
	v_cndmask_b32_e32 v35, v78, v75, vcc
	v_mul_f32_e32 v36, v35, v34
	v_cmp_gt_f32_e32 vcc, s69, v36
	s_nop 1
	v_cndmask_b32_e32 v36, 0, v183, vcc
	v_fmac_f32_e32 v36, v35, v34
	v_exp_f32_e32 v34, v36
	v_cndmask_b32_e32 v35, 0, v184, vcc
	v_ldexp_f32 v63, v34, v35
	v_or_b32_e32 v34, 0x53, v73
	v_cmp_gt_i32_e32 vcc, v34, v70
	v_sub_u32_e32 v34, v34, v70
	v_sub_u32_e32 v35, 0, v34
	v_max_i32_e32 v34, v34, v35
	v_cvt_f32_u32_e32 v34, v34
	v_cndmask_b32_e32 v35, v78, v75, vcc
	v_mul_f32_e32 v36, v35, v34
	v_cmp_gt_f32_e32 vcc, s69, v36
	s_nop 1
	v_cndmask_b32_e32 v36, 0, v183, vcc
	v_fmac_f32_e32 v36, v35, v34
	v_exp_f32_e32 v34, v36
	v_cndmask_b32_e32 v35, 0, v184, vcc
	v_cmp_gt_i32_e32 vcc, v39, v70
	v_sub_u32_e32 v39, v39, v70
	v_sub_u32_e32 v40, 0, v39
	v_ldexp_f32 v65, v34, v35
	ds_read_b128 v[34:37], v38 offset:32256
	v_max_i32_e32 v39, v39, v40
	v_cvt_f32_u32_e32 v39, v39
	v_cndmask_b32_e32 v40, v78, v75, vcc
	s_waitcnt lgkmcnt(0)
	v_mfma_f32_16x16x32_bf16 v[34:37], v[34:37], v[6:9], 0
	v_mul_f32_e32 v41, v40, v39
	v_cmp_gt_f32_e32 vcc, s69, v41
	v_mfma_f32_16x16x32_bf16 v[34:37], v[66:69], v[2:5], v[34:37]
	s_nop 0
	v_cndmask_b32_e32 v41, 0, v183, vcc
	v_fmac_f32_e32 v41, v40, v39
	v_exp_f32_e32 v39, v41
	v_cndmask_b32_e32 v40, 0, v184, vcc
	v_ldexp_f32 v66, v39, v40
	v_or_b32_e32 v39, 0x61, v73
	v_cmp_gt_i32_e32 vcc, v39, v70
	v_sub_u32_e32 v39, v39, v70
	v_sub_u32_e32 v40, 0, v39
	v_max_i32_e32 v39, v39, v40
	v_cvt_f32_u32_e32 v39, v39
	v_cndmask_b32_e32 v40, v78, v75, vcc
	v_mul_f32_e32 v41, v40, v39
	v_cmp_gt_f32_e32 vcc, s69, v41
	s_nop 1
	v_cndmask_b32_e32 v41, 0, v183, vcc
	v_fmac_f32_e32 v41, v40, v39
	v_exp_f32_e32 v39, v41
	v_cndmask_b32_e32 v40, 0, v184, vcc
	v_ldexp_f32 v68, v39, v40
	v_or_b32_e32 v39, 0x62, v73
	v_cmp_gt_i32_e32 vcc, v39, v70
	v_sub_u32_e32 v39, v39, v70
	v_sub_u32_e32 v40, 0, v39
	v_max_i32_e32 v39, v39, v40
	v_cvt_f32_u32_e32 v39, v39
	v_cndmask_b32_e32 v40, v78, v75, vcc
	v_mul_f32_e32 v41, v40, v39
	v_cmp_gt_f32_e32 vcc, s69, v41
	s_nop 1
	v_cndmask_b32_e32 v41, 0, v183, vcc
	v_fmac_f32_e32 v41, v40, v39
	v_exp_f32_e32 v39, v41
	v_cndmask_b32_e32 v40, 0, v184, vcc
	v_ldexp_f32 v67, v39, v40
	v_or_b32_e32 v39, 0x63, v73
	v_cmp_gt_i32_e32 vcc, v39, v70
	v_sub_u32_e32 v39, v39, v70
	v_sub_u32_e32 v40, 0, v39
	v_max_i32_e32 v39, v39, v40
	v_cvt_f32_u32_e32 v39, v39
	v_cndmask_b32_e32 v40, v78, v75, vcc
	v_mul_f32_e32 v41, v40, v39
	v_cmp_gt_f32_e32 vcc, s69, v41
	s_nop 1
	v_cndmask_b32_e32 v41, 0, v183, vcc
	v_fmac_f32_e32 v41, v40, v39
	v_cndmask_b32_e32 v40, 0, v184, vcc
	v_cmp_gt_i32_e32 vcc, v74, v70
	v_sub_u32_e32 v74, v74, v70
	v_sub_u32_e32 v76, 0, v74
	v_max_i32_e32 v74, v74, v76
	v_cvt_f32_u32_e32 v74, v74
	v_cndmask_b32_e32 v76, v78, v75, vcc
	v_exp_f32_e32 v39, v41
	v_mul_f32_e32 v77, v76, v74
	v_cmp_gt_f32_e32 vcc, s69, v77
	v_ldexp_f32 v69, v39, v40
	ds_read_b128 v[38:41], v38 offset:34624
	v_cndmask_b32_e32 v77, 0, v183, vcc
	v_fmac_f32_e32 v77, v76, v74
	v_exp_f32_e32 v74, v77
	v_cndmask_b32_e32 v76, 0, v184, vcc
	s_waitcnt lgkmcnt(0)
	v_mfma_f32_16x16x32_bf16 v[38:41], v[38:41], v[2:5], v[80:83]
	v_ldexp_f32 v76, v74, v76
	v_or_b32_e32 v74, 0x71, v73
	v_cmp_gt_i32_e32 vcc, v74, v70
	v_sub_u32_e32 v74, v74, v70
	v_sub_u32_e32 v77, 0, v74
	v_max_i32_e32 v74, v74, v77
	v_cvt_f32_u32_e32 v74, v74
	v_cndmask_b32_e32 v77, v78, v75, vcc
	v_mov_b32_e32 v82, v35
	v_mov_b32_e32 v35, v36
	v_mul_f32_e32 v79, v77, v74
	v_cmp_gt_f32_e32 vcc, s69, v79
	v_mov_b32_e32 v36, v31
	v_mov_b32_e32 v31, v32
	v_cndmask_b32_e32 v79, 0, v183, vcc
	v_fmac_f32_e32 v79, v77, v74
	v_exp_f32_e32 v74, v79
	v_cndmask_b32_e32 v77, 0, v184, vcc
	v_mov_b32_e32 v32, v27
	v_mov_b32_e32 v27, v28
	v_ldexp_f32 v80, v74, v77
	v_or_b32_e32 v74, 0x72, v73
	v_cmp_gt_i32_e32 vcc, v74, v70
	v_sub_u32_e32 v74, v74, v70
	v_sub_u32_e32 v77, 0, v74
	v_max_i32_e32 v74, v74, v77
	v_cvt_f32_u32_e32 v74, v74
	v_cndmask_b32_e32 v77, v78, v75, vcc
	v_or_b32_e32 v73, 0x73, v73
	v_pk_mul_f32 v[58:59], v[58:59], v[26:27]
	v_mul_f32_e32 v79, v77, v74
	v_cmp_gt_f32_e32 vcc, s69, v79
	v_mov_b32_e32 v26, v23
	v_mov_b32_e32 v23, v24
	v_cndmask_b32_e32 v79, 0, v183, vcc
	v_fmac_f32_e32 v79, v77, v74
	v_exp_f32_e32 v74, v79
	v_cndmask_b32_e32 v77, 0, v184, vcc
	v_cmp_gt_i32_e32 vcc, v73, v70
	v_sub_u32_e32 v73, v73, v70
	v_ldexp_f32 v77, v74, v77
	v_sub_u32_e32 v74, 0, v73
	v_mov_b32_e32 v83, v37
	v_mov_b32_e32 v37, v33
	v_mov_b32_e32 v33, v29
	v_pk_mul_f32 v[28:29], v[54:55], v[22:23]
	v_mov_b32_e32 v22, v19
; __device__ __forceinline__ unsigned pk2(float lo, float hi) { return f2bf(lo) | (f2bf(hi) << 16); }
; #define MFMA16(a, b, c) __builtin_amdgcn_mfma_f32_16x16x32_bf16(a, b, c, 0, 0, 0)
; __device__ __forceinline__ void ret2_task(const Params& p_, int l, int task, unsigned char* lds) {
;     ...
;         for (int r = 0; r < 4; ++r) { const int aj = 16 * jt + 4 * fq + r; const float wg = (aj <= ai) ? exp2f(l2f * (float)(ai - aj)) : exp2f(l2b * (float)(aj - ai)); sc[r] = acc[r] * wg; }
;         pp[jt][0] = pk2(sc[0], sc[1]); pp[jt][1] = pk2(sc[2], sc[3]); }
;     const float qdf = exp2f(l2f * (float)(ai + 1)), qdb = exp2f(l2b * (float)(128 - ai));
;     f32x4 tot[4]; float ss = 0.f;
; #pragma unroll
;     for (int et = 0; et < 4; ++et) { f32x4 o = {0.f, 0.f, 0.f, 0.f}, cfa = o, cba = o;
; #pragma unroll
;         for (int t = 0; t < 4; ++t) { const u32x2 vlo = *(const u32x2*)(VT + (16 * et + fr) * 136 + 32 * t + 4 * fq), vhi = *(const u32x2*)(VT + (16 * et + fr) * 136 + 32 * t + 16 + 4 * fq);
;             o = MFMA16(mk8(vlo.x, vlo.y, vhi.x, vhi.y), mk8(pp[2 * t][0], pp[2 * t][1], pp[2 * t + 1][0], pp[2 * t + 1][1]), o); }
; #pragma unroll
;         for (int ks = 0; ks < 2; ++ks) { const bf16x8v sf = *(const bf16x8v*)(STF + (16 * et + fr) * 72 + 32 * ks + 8 * fq), sb = *(const bf16x8v*)(STB + (16 * et + fr) * 72 + 32 * ks + 8 * fq);
;             cfa = MFMA16(sf, qf[ks], cfa); cba = MFMA16(sb, qf[ks], cba); }
	v_mov_b32_e32 v19, v20
	v_max_i32_e32 v73, v73, v74
	v_pk_mul_f32 v[50:51], v[50:51], v[18:19]
	v_mov_b32_e32 v18, v15
	v_mov_b32_e32 v15, v16
	v_cvt_f32_u32_e32 v73, v73
	v_mov_b32_e32 v23, v21
	v_pk_mul_f32 v[20:21], v[46:47], v[14:15]
	v_mov_b32_e32 v14, v11
	v_mov_b32_e32 v15, v13
	v_mov_b32_e32 v11, v12
	v_mov_b32_e32 v12, v38
	v_mov_b32_e32 v13, v40
	v_pk_mul_f32 v[10:11], v[42:43], v[10:11]
	v_pk_mul_f32 v[42:43], v[76:77], v[12:13]
	v_add_u32_e32 v12, 1, v70
	v_cvt_f32_i32_e32 v12, v12
	v_cndmask_b32_e32 v74, v78, v75, vcc
	v_mul_f32_e32 v79, v74, v73
	v_cmp_gt_f32_e32 vcc, s69, v79
	v_mul_f32_e32 v13, v78, v12
	v_mov_b32_e32 v40, v39
	v_cndmask_b32_e32 v79, 0, v183, vcc
	v_fmac_f32_e32 v79, v74, v73
	v_cndmask_b32_e32 v74, 0, v184, vcc
	v_cmp_gt_f32_e32 vcc, s69, v13
	v_exp_f32_e32 v73, v79
	v_pk_mul_f32 v[52:53], v[52:53], v[22:23]
	v_cndmask_b32_e32 v13, 0, v183, vcc
	v_fmac_f32_e32 v13, v78, v12
	v_exp_f32_e32 v12, v13
	v_cndmask_b32_e32 v13, 0, v184, vcc
	v_ldexp_f32 v81, v73, v74
	v_pk_mul_f32 v[22:23], v[44:45], v[14:15]
	v_ldexp_f32 v38, v12, v13
	v_sub_u32_e32 v12, 0x80, v70
	v_cvt_f32_i32_e32 v12, v12
	v_pk_mul_f32 v[44:45], v[80:81], v[40:41]
	v_mov_b32_e32 v19, v17
	v_pk_mul_f32 v[18:19], v[48:49], v[18:19]
	v_mul_f32_e32 v13, v75, v12
	v_cmp_gt_f32_e32 vcc, s69, v13
	v_mov_b32_e32 v27, v25
	v_bfe_u32 v24, v23, 16, 1
	v_cndmask_b32_e32 v13, 0, v183, vcc
	v_fmac_f32_e32 v13, v75, v12
	v_exp_f32_e32 v12, v13
	v_cndmask_b32_e32 v13, 0, v184, vcc
	v_bfe_u32 v25, v22, 16, 1
	v_add3_u32 v22, v22, v25, s14
	v_ldexp_f32 v40, v12, v13
	v_mul_u32_u24_e32 v12, 0x110, v71
	v_add3_u32 v39, 0, v12, v0
	v_add_u32_e32 v41, 0x9000, v39
	ds_read_b64 v[14:15], v41
	ds_read_b64 v[16:17], v41 offset:32
	v_bfe_u32 v12, v19, 16, 1
	v_bfe_u32 v13, v18, 16, 1
	v_add3_u32 v18, v18, v13, s14
	v_add3_u32 v12, v19, v12, s14
	v_bfe_u32 v13, v10, 16, 1
	v_bfe_u32 v19, v11, 16, 1
	v_add3_u32 v11, v11, v19, s14
	v_add3_u32 v10, v10, v13, s14
	v_add3_u32 v23, v23, v24, s14
	v_bfe_u32 v24, v20, 16, 1
	v_bfe_u32 v25, v21, 16, 1
	v_lshrrev_b32_e32 v10, 16, v10
	v_lshrrev_b32_e32 v11, 16, v11
	v_add3_u32 v21, v21, v25, s14
	v_add3_u32 v20, v20, v24, s14
	v_and_or_b32 v11, v23, s15, v11
	v_and_or_b32 v10, v22, s15, v10
	ds_read_b64 v[22:23], v41 offset:64
	ds_read_b64 v[24:25], v41 offset:96
	v_lshrrev_b32_e32 v19, 16, v20
	v_lshrrev_b32_e32 v13, 16, v21
	v_pk_mul_f32 v[26:27], v[56:57], v[26:27]
	v_and_or_b32 v13, v12, s15, v13
	v_and_or_b32 v12, v18, s15, v19
	v_pk_mul_f32 v[36:37], v[64:65], v[36:37]
	v_pk_mul_f32 v[32:33], v[60:61], v[32:33]
	s_waitcnt lgkmcnt(2)
	v_mfma_f32_16x16x32_bf16 v[18:21], v[14:17], v[10:13], 0
	v_bfe_u32 v14, v27, 16, 1
	v_bfe_u32 v15, v26, 16, 1
	v_bfe_u32 v16, v53, 16, 1
	v_bfe_u32 v17, v52, 16, 1
	v_add3_u32 v46, v52, v17, s14
	v_add3_u32 v47, v53, v16, s14
	v_add3_u32 v15, v26, v15, s14
	v_add3_u32 v14, v27, v14, s14
	v_bfe_u32 v16, v50, 16, 1
	v_bfe_u32 v17, v51, 16, 1
	v_bfe_u32 v26, v28, 16, 1
	v_bfe_u32 v27, v29, 16, 1
	v_add3_u32 v27, v29, v27, s14
	v_add3_u32 v26, v28, v26, s14
	v_add3_u32 v17, v51, v17, s14
	v_add3_u32 v16, v50, v16, s14
	v_lshrrev_b32_e32 v28, 16, v16
	v_lshrrev_b32_e32 v29, 16, v17
	v_lshrrev_b32_e32 v16, 16, v26
	v_lshrrev_b32_e32 v17, 16, v27
	v_and_or_b32 v17, v14, s15, v17
	v_and_or_b32 v16, v15, s15, v16
	v_and_or_b32 v15, v47, s15, v29
	v_and_or_b32 v14, v46, s15, v28
	ds_read_b64 v[26:27], v41 offset:128
	ds_read_b64 v[28:29], v41 offset:160
	v_pk_mul_f32 v[30:31], v[62:63], v[30:31]
	s_waitcnt lgkmcnt(2)
	v_mfma_f32_16x16x32_bf16 v[18:21], v[22:25], v[14:17], v[18:21]
	v_bfe_u32 v22, v37, 16, 1
	v_bfe_u32 v23, v36, 16, 1
	v_bfe_u32 v24, v33, 16, 1
	v_bfe_u32 v25, v32, 16, 1
	v_add3_u32 v32, v32, v25, s14
	v_add3_u32 v33, v33, v24, s14
	v_add3_u32 v23, v36, v23, s14
	v_add3_u32 v22, v37, v22, s14
	v_bfe_u32 v24, v58, 16, 1
	v_bfe_u32 v25, v59, 16, 1
	v_bfe_u32 v36, v30, 16, 1
	v_bfe_u32 v37, v31, 16, 1
	v_add3_u32 v31, v31, v37, s14
	v_add3_u32 v30, v30, v36, s14
	v_add3_u32 v25, v59, v25, s14
	v_add3_u32 v24, v58, v24, s14
	v_lshrrev_b32_e32 v36, 16, v24
	v_lshrrev_b32_e32 v37, 16, v25
	v_lshrrev_b32_e32 v24, 16, v30
	v_lshrrev_b32_e32 v25, 16, v31
	v_and_or_b32 v25, v22, s15, v25
	v_and_or_b32 v24, v23, s15, v24
	v_and_or_b32 v23, v33, s15, v37
	v_and_or_b32 v22, v32, s15, v36
	ds_read_b64 v[30:31], v41 offset:192
	ds_read_b64 v[32:33], v41 offset:224
	v_pk_mul_f32 v[68:69], v[68:69], v[82:83]
	v_pk_mul_f32 v[34:35], v[66:67], v[34:35]
	s_waitcnt lgkmcnt(2)
	v_mfma_f32_16x16x32_bf16 v[26:29], v[26:29], v[22:25], v[18:21]
	v_bfe_u32 v41, v42, 16, 1
	v_add3_u32 v41, v42, v41, s14
	v_add_u32_e32 v47, 0xb000, v39
	v_bfe_u32 v19, v44, 16, 1
	v_bfe_u32 v20, v69, 16, 1
	v_bfe_u32 v21, v68, 16, 1
	v_add3_u32 v36, v68, v21, s14
	v_add3_u32 v37, v69, v20, s14
	v_add3_u32 v19, v44, v19, s14
	v_bfe_u32 v20, v34, 16, 1
	v_bfe_u32 v21, v35, 16, 1
	v_bfe_u32 v44, v43, 16, 1
	v_bfe_u32 v18, v45, 16, 1
	v_add3_u32 v43, v43, v44, s14
	v_add3_u32 v21, v35, v21, s14
	v_add3_u32 v20, v34, v20, s14
	v_add3_u32 v18, v45, v18, s14
	v_lshrrev_b32_e32 v34, 16, v20
	v_lshrrev_b32_e32 v35, 16, v21
	v_lshrrev_b32_e32 v20, 16, v41
	v_lshrrev_b32_e32 v21, 16, v43
	v_and_or_b32 v21, v18, s15, v21
	v_and_or_b32 v20, v19, s15, v20
	v_and_or_b32 v19, v37, s15, v35
	v_and_or_b32 v18, v36, s15, v34
	s_waitcnt lgkmcnt(0)
	s_nop 0
	v_mfma_f32_16x16x32_bf16 v[26:29], v[30:33], v[18:21], v[26:29]
	v_mul_u32_u24_e32 v30, 0x48, v71
	v_lshlrev_b32_e32 v30, 1, v30
	v_add3_u32 v41, s6, v72, v30
	v_add3_u32 v46, s24, v72, v30
	ds_read_b128 v[30:33], v41
	ds_read_b128 v[34:37], v46
	s_waitcnt lgkmcnt(1)
; #define MFMA16(a, b, c) __builtin_amdgcn_mfma_f32_16x16x32_bf16(a, b, c, 0, 0, 0)
; __device__ __forceinline__ void ret2_task(const Params& p_, int l, int task, unsigned char* lds) {
;     ...
;     for (int et = 0; et < 4; ++et) { f32x4 o = {0.f, 0.f, 0.f, 0.f}, cfa = o, cba = o;
; #pragma unroll
;         for (int t = 0; t < 4; ++t) { const u32x2 vlo = *(const u32x2*)(VT + (16 * et + fr) * 136 + 32 * t + 4 * fq), vhi = *(const u32x2*)(VT + (16 * et + fr) * 136 + 32 * t + 16 + 4 * fq);
;             o = MFMA16(mk8(vlo.x, vlo.y, vhi.x, vhi.y), mk8(pp[2 * t][0], pp[2 * t][1], pp[2 * t + 1][0], pp[2 * t + 1][1]), o); }
; #pragma unroll
;         for (int ks = 0; ks < 2; ++ks) { const bf16x8v sf = *(const bf16x8v*)(STF + (16 * et + fr) * 72 + 32 * ks + 8 * fq), sb = *(const bf16x8v*)(STB + (16 * et + fr) * 72 + 32 * ks + 8 * fq);
;             cfa = MFMA16(sf, qf[ks], cfa); cba = MFMA16(sb, qf[ks], cba); }
;         tot[et] = o + cfa * qdf + cba * qdb;
;         ss += (tot[et][0] * tot[et][0] + tot[et][1] * tot[et][1]) + (tot[et][2] * tot[et][2] + tot[et][3] * tot[et][3]); }
	v_mfma_f32_16x16x32_bf16 v[30:33], v[30:33], v[6:9], 0
	ds_read_b128 v[42:45], v41 offset:64
	ds_read_b128 v[48:51], v46 offset:64
	s_or_b32 s6, s43, s42
	s_lshl_b32 s24, s44, 1
	s_waitcnt lgkmcnt(2)
	v_mfma_f32_16x16x32_bf16 v[34:37], v[34:37], v[6:9], 0
	s_cmpk_lt_i32 s10, 0x200
	s_waitcnt lgkmcnt(1)
	v_mfma_f32_16x16x32_bf16 v[30:33], v[42:45], v[2:5], v[30:33]
	s_waitcnt lgkmcnt(0)
	v_mfma_f32_16x16x32_bf16 v[42:45], v[48:51], v[2:5], v[34:37]
	s_nop 5
	v_fma_f32 v28, v38, v32, v28
	v_fma_f32 v29, v38, v33, v29
	v_pk_fma_f32 v[26:27], v[38:39], v[30:31], v[26:27] op_sel_hi:[0,1,1]
	v_pk_fma_f32 v[34:35], v[40:41], v[44:45], v[28:29] op_sel_hi:[0,1,1]
	v_pk_fma_f32 v[36:37], v[40:41], v[42:43], v[26:27] op_sel_hi:[0,1,1]
	v_pk_mul_f32 v[26:27], v[34:35], v[34:35]
	v_pk_mul_f32 v[28:29], v[36:37], v[36:37]
	v_add_u32_e32 v44, 0xa000, v39
	v_pk_mov_b32 v[30:31], v[28:29], v[26:27] op_sel:[1,0]
	v_mov_b32_e32 v29, v27
	v_pk_add_f32 v[42:43], v[30:31], v[28:29]
	ds_read_b64 v[26:27], v44 offset:256
	ds_read_b64 v[28:29], v44 offset:288
	ds_read_b64 v[30:31], v44 offset:320
	ds_read_b64 v[32:33], v44 offset:352
	s_waitcnt lgkmcnt(2)
	v_mfma_f32_16x16x32_bf16 v[26:29], v[26:29], v[10:13], 0
	s_waitcnt lgkmcnt(0)
	v_mfma_f32_16x16x32_bf16 v[26:29], v[30:33], v[14:17], v[26:29]
	ds_read_b64 v[30:31], v44 offset:384
	ds_read_b64 v[32:33], v44 offset:416
	s_waitcnt lgkmcnt(0)
	v_mfma_f32_16x16x32_bf16 v[26:29], v[30:33], v[22:25], v[26:29]
	ds_read_b64 v[30:31], v44 offset:448
	ds_read_b64 v[32:33], v44 offset:480
	s_waitcnt lgkmcnt(0)
	v_mfma_f32_16x16x32_bf16 v[26:29], v[30:33], v[18:21], v[26:29]
	ds_read_b128 v[30:33], v41 offset:2304
	ds_read_b128 v[48:51], v46 offset:2304
	ds_read_b128 v[52:55], v41 offset:2368
	ds_read_b128 v[56:59], v46 offset:2368
	s_waitcnt lgkmcnt(3)
	v_mfma_f32_16x16x32_bf16 v[30:33], v[30:33], v[6:9], 0
	s_waitcnt lgkmcnt(2)
	v_mfma_f32_16x16x32_bf16 v[48:51], v[48:51], v[6:9], 0
	s_waitcnt lgkmcnt(1)
	v_mfma_f32_16x16x32_bf16 v[30:33], v[52:55], v[2:5], v[30:33]
	s_waitcnt lgkmcnt(0)
	v_mfma_f32_16x16x32_bf16 v[48:51], v[56:59], v[2:5], v[48:51]
	s_nop 5
	v_fma_f32 v28, v38, v32, v28
	v_fma_f32 v29, v38, v33, v29
	v_pk_fma_f32 v[26:27], v[38:39], v[30:31], v[26:27] op_sel_hi:[0,1,1]
	v_pk_fma_f32 v[30:31], v[40:41], v[50:51], v[28:29] op_sel_hi:[0,1,1]
	v_pk_fma_f32 v[32:33], v[40:41], v[48:49], v[26:27] op_sel_hi:[0,1,1]
	v_pk_mul_f32 v[26:27], v[30:31], v[30:31]
	v_pk_mul_f32 v[28:29], v[32:33], v[32:33]
	ds_read_b64 v[48:49], v47 offset:576
	ds_read_b64 v[50:51], v47 offset:608
	v_pk_mov_b32 v[44:45], v[28:29], v[26:27] op_sel:[1,0]
	v_mov_b32_e32 v29, v27
	v_pk_add_f32 v[44:45], v[44:45], v[28:29]
	ds_read_b64 v[26:27], v47 offset:512
	ds_read_b64 v[28:29], v47 offset:544
	s_waitcnt lgkmcnt(0)
	v_mfma_f32_16x16x32_bf16 v[26:29], v[26:29], v[10:13], 0
	v_mfma_f32_16x16x32_bf16 v[26:29], v[48:51], v[14:17], v[26:29]
	ds_read_b64 v[48:49], v47 offset:640
	ds_read_b64 v[50:51], v47 offset:672
	s_waitcnt lgkmcnt(0)
	v_mfma_f32_16x16x32_bf16 v[26:29], v[48:51], v[22:25], v[26:29]
	ds_read_b64 v[48:49], v47 offset:704
	ds_read_b64 v[50:51], v47 offset:736
	s_waitcnt lgkmcnt(0)
	v_mfma_f32_16x16x32_bf16 v[26:29], v[48:51], v[18:21], v[26:29]
	ds_read_b128 v[48:51], v41 offset:4608
	ds_read_b128 v[52:55], v46 offset:4608
	ds_read_b128 v[56:59], v41 offset:4672
	ds_read_b128 v[60:63], v46 offset:4672
	s_waitcnt lgkmcnt(3)
	v_mfma_f32_16x16x32_bf16 v[48:51], v[48:51], v[6:9], 0
	s_waitcnt lgkmcnt(2)
	v_mfma_f32_16x16x32_bf16 v[52:55], v[52:55], v[6:9], 0
	s_waitcnt lgkmcnt(1)
	v_mfma_f32_16x16x32_bf16 v[48:51], v[56:59], v[2:5], v[48:51]
	s_waitcnt lgkmcnt(0)
	v_mfma_f32_16x16x32_bf16 v[52:55], v[60:63], v[2:5], v[52:55]
	s_nop 5
	v_fma_f32 v28, v38, v50, v28
	v_fma_f32 v29, v38, v51, v29
	v_pk_fma_f32 v[48:49], v[38:39], v[48:49], v[26:27] op_sel_hi:[0,1,1]
	v_add_u32_e32 v39, 0xc000, v39
	v_pk_fma_f32 v[26:27], v[40:41], v[54:55], v[28:29] op_sel_hi:[0,1,1]
	v_pk_fma_f32 v[28:29], v[40:41], v[52:53], v[48:49] op_sel_hi:[0,1,1]
	ds_read_b64 v[48:49], v39 offset:768
	ds_read_b64 v[50:51], v39 offset:800
	s_waitcnt lgkmcnt(0)
	v_mfma_f32_16x16x32_bf16 v[10:13], v[48:51], v[10:13], 0
	ds_read_b64 v[48:49], v39 offset:832
	ds_read_b64 v[50:51], v39 offset:864
	s_waitcnt lgkmcnt(0)
	v_mfma_f32_16x16x32_bf16 v[10:13], v[48:51], v[14:17], v[10:13]
	ds_read_b64 v[14:15], v39 offset:896
	ds_read_b64 v[16:17], v39 offset:928
	s_waitcnt lgkmcnt(0)
	v_mfma_f32_16x16x32_bf16 v[10:13], v[14:17], v[22:25], v[10:13]
	ds_read_b64 v[14:15], v39 offset:960
	ds_read_b64 v[16:17], v39 offset:992
	s_waitcnt lgkmcnt(0)
	v_mfma_f32_16x16x32_bf16 v[10:13], v[14:17], v[18:21], v[10:13]
	ds_read_b128 v[14:17], v41 offset:6912
	ds_read_b128 v[18:21], v46 offset:6912
	s_waitcnt lgkmcnt(1)
	v_mfma_f32_16x16x32_bf16 v[14:17], v[14:17], v[6:9], 0
	s_waitcnt lgkmcnt(0)
	v_mfma_f32_16x16x32_bf16 v[6:9], v[18:21], v[6:9], 0
	ds_read_b128 v[18:21], v41 offset:6976
	ds_read_b128 v[22:25], v46 offset:6976
	s_waitcnt lgkmcnt(1)
	v_mfma_f32_16x16x32_bf16 v[14:17], v[18:21], v[2:5], v[14:17]
	v_mov_b32_e32 v18, v36
	v_mov_b32_e32 v19, v34
	v_mov_b32_e32 v34, v37
	s_waitcnt lgkmcnt(0)
; __device__ __forceinline__ unsigned pk2(float lo, float hi) { return f2bf(lo) | (f2bf(hi) << 16); }
; __device__ __forceinline__ float bflo(unsigned u) { return __uint_as_float(u << 16); }
; __device__ __forceinline__ float bfhi(unsigned u) { return __uint_as_float(u & 0xffff0000u); }
; __device__ __forceinline__ float silu_f(float v) { return v / (1.f + __expf(-v)); }
; __device__ __forceinline__ void ret2_task(const Params& p_, int l, int task, unsigned char* lds) {
;     ...
;         ss += (tot[et][0] * tot[et][0] + tot[et][1] * tot[et][1]) + (tot[et][2] * tot[et][2] + tot[et][3] * tot[et][3]); }
;     ss += __shfl_xor(ss, 16); ss += __shfl_xor(ss, 32);
;     const float rs = rsqrtf(ss * (1.f / 64.f) + 1e-6f);
;     const size_t tok = (size_t)b * SEQ + n * 128 + ai;
;     const bf16* Z = (const bf16*)(p.ws + WS_Z); bf16* CAT = (bf16*)(p.ws + WS_CAT);
; #pragma unroll
;     for (int et = 0; et < 4; ++et) { const u32x2 gz = *(const u32x2*)(Z + tok * DIN + 9 * DG + h * 64 + 16 * et + 4 * fq); u32x2 o;
;         o.x = pk2(tot[et][0] * rs * silu_f(bflo(gz.x)), tot[et][1] * rs * silu_f(bfhi(gz.x))); o.y = pk2(tot[et][2] * rs * silu_f(bflo(gz.y)), tot[et][3] * rs * silu_f(bfhi(gz.y)));
;         *(u32x2*)(CAT + tok * DM + 1024 + h * 64 + 16 * et + 4 * fq) = o; }
	v_mfma_f32_16x16x32_bf16 v[4:7], v[22:25], v[2:5], v[6:9]
	s_nop 2
	v_fma_f32 v2, v38, v16, v12
	v_fma_f32 v3, v38, v17, v13
	v_pk_fma_f32 v[8:9], v[38:39], v[14:15], v[10:11] op_sel_hi:[0,1,1]
	s_nop 1
	v_pk_fma_f32 v[4:5], v[40:41], v[4:5], v[8:9] op_sel_hi:[0,1,1]
	v_pk_fma_f32 v[2:3], v[40:41], v[6:7], v[2:3] op_sel_hi:[0,1,1]
	v_mul_f32_e32 v8, v4, v4
	v_pk_add_f32 v[6:7], v[42:43], v[42:43] op_sel:[0,1] op_sel_hi:[1,0]
	v_mul_f32_e32 v10, v5, v5
	v_mov_b32_e32 v7, v8
	v_pk_add_f32 v[8:9], v[44:45], v[44:45] op_sel:[0,1] op_sel_hi:[1,0]
	v_mul_f32_e32 v11, v2, v2
	v_mov_b32_e32 v9, v10
	v_pk_add_f32 v[6:7], v[6:7], v[8:9]
	v_mul_f32_e32 v8, v29, v29
	v_pk_fma_f32 v[8:9], v[28:29], v[28:29], v[8:9] op_sel_hi:[1,1,0]
	v_mul_f32_e32 v10, v27, v27
	v_mul_f32_e32 v12, v3, v3
	v_mov_b32_e32 v9, v11
	v_pk_fma_f32 v[10:11], v[26:27], v[26:27], v[10:11] op_sel_hi:[1,1,0]
	s_nop 0
	v_mov_b32_e32 v11, v12
	v_pk_add_f32 v[8:9], v[8:9], v[10:11]
	s_nop 0
	v_pk_add_f32 v[6:7], v[6:7], v[8:9]
	v_and_b32_e32 v8, 64, v178
	v_add_f32_e32 v6, v6, v7
	v_xor_b32_e32 v7, 16, v178
	v_add_u32_e32 v8, 64, v8
	v_cmp_lt_i32_e32 vcc, v7, v8
	s_nop 1
	v_cndmask_b32_e32 v7, v178, v7, vcc
	v_lshlrev_b32_e32 v7, 2, v7
	ds_bpermute_b32 v7, v7, v6
	s_waitcnt lgkmcnt(0)
	v_add_f32_e32 v6, v6, v7
	v_xor_b32_e32 v7, 32, v178
	v_cmp_lt_i32_e32 vcc, v7, v8
	v_mov_b64_e32 v[8:9], s[36:37]
	s_nop 0
	v_cndmask_b32_e32 v7, v178, v7, vcc
	v_lshlrev_b32_e32 v7, 2, v7
	ds_bpermute_b32 v7, v7, v6
	s_waitcnt lgkmcnt(0)
	v_add_f32_e32 v6, v6, v7
	v_fmamk_f32 v6, v6, 0x3c800000, v146
	v_cmp_gt_f32_e32 vcc, s92, v6
	v_mul_f32_e32 v7, 0x4b800000, v6
	s_nop 0
	v_cndmask_b32_e32 v6, v6, v7, vcc
	v_rsq_f32_e32 v6, v6
	s_nop 0
	v_mul_f32_e32 v7, 0x45800000, v6
	v_cndmask_b32_e32 v6, v6, v7, vcc
	v_add_u32_e32 v7, s6, v70
	v_mad_i64_i32 v[8:9], s[12:13], v7, s75, v[8:9]
	v_lshl_add_u64 v[10:11], v[8:9], 0, s[24:25]
	v_lshl_add_u64 v[12:13], v[10:11], 0, v[0:1]
	s_mov_b64 s[12:13], 0xad22400
	s_movk_i32 s6, 0xdc00
	v_lshl_add_u64 v[10:11], v[12:13], 0, s[12:13]
	v_mad_i64_i32 v[8:9], s[12:13], v7, s6, v[8:9]
	s_mov_b32 s6, 0xad22000
	v_add_co_u32_e32 v12, vcc, s6, v12
	v_lshl_add_u64 v[8:9], v[8:9], 0, s[24:25]
	s_nop 0
	v_addc_co_u32_e32 v13, vcc, 0, v13, vcc
	global_load_dwordx2 v[12:13], v[12:13], off offset:1024
	v_lshl_add_u64 v[14:15], v[8:9], 0, v[0:1]
	s_mov_b64 s[12:13], 0x12d20800
	v_lshl_add_u64 v[8:9], v[14:15], 0, s[12:13]
	s_mov_b32 s6, 0x12d20000
	s_waitcnt vmcnt(0)
	v_lshlrev_b32_e32 v0, 16, v13
	v_lshlrev_b32_e32 v7, 16, v12
	v_mul_f32_e32 v16, 0xbfb8aa3b, v7
	v_and_b32_e32 v20, 0xffff0000, v13
	v_mul_f32_e32 v13, 0xbfb8aa3b, v0
	v_exp_f32_e32 v16, v16
	v_exp_f32_e32 v17, v13
	v_and_b32_e32 v21, 0xffff0000, v12
	v_mul_f32_e32 v12, 0xbfb8aa3b, v21
	v_exp_f32_e32 v12, v12
	v_pk_add_f32 v[16:17], v[16:17], 1.0 op_sel_hi:[1,0]
	v_pk_mul_f32 v[18:19], v[18:19], v[6:7] op_sel_hi:[1,0]
	v_div_scale_f32 v13, s[12:13], v17, v17, v0
	v_rcp_f32_e32 v22, v13
	s_nop 0
	v_fma_f32 v23, -v13, v22, 1.0
	v_fmac_f32_e32 v22, v23, v22
	v_div_scale_f32 v23, vcc, v0, v17, v0
	v_mul_f32_e32 v24, v23, v22
	v_fma_f32 v25, -v13, v24, v23
	v_fmac_f32_e32 v24, v25, v22
	v_fma_f32 v13, -v13, v24, v23
	v_div_fmas_f32 v13, v13, v22, v24
	v_div_fixup_f32 v17, v13, v17, v0
	v_div_scale_f32 v0, s[12:13], v16, v16, v7
	v_rcp_f32_e32 v13, v0
	s_nop 0
	v_fma_f32 v22, -v0, v13, 1.0
	v_fmac_f32_e32 v13, v22, v13
	v_div_scale_f32 v22, vcc, v7, v16, v7
	v_mul_f32_e32 v23, v22, v13
	v_fma_f32 v24, -v0, v23, v22
	v_fmac_f32_e32 v23, v24, v13
	v_fma_f32 v0, -v0, v23, v22
	v_div_fmas_f32 v0, v0, v13, v23
	v_div_fixup_f32 v16, v0, v16, v7
	v_mul_f32_e32 v0, 0xbfb8aa3b, v20
	v_exp_f32_e32 v13, v0
	v_pk_mul_f32 v[16:17], v[16:17], v[18:19]
	v_pk_mul_f32 v[18:19], v[34:35], v[6:7] op_sel_hi:[1,0]
	v_pk_add_f32 v[12:13], v[12:13], 1.0 op_sel_hi:[1,0]
	s_nop 0
	v_div_scale_f32 v0, s[12:13], v13, v13, v20
	v_rcp_f32_e32 v7, v0
	s_nop 0
	v_fma_f32 v22, -v0, v7, 1.0
	v_fmac_f32_e32 v7, v22, v7
	v_div_scale_f32 v22, vcc, v20, v13, v20
	v_mul_f32_e32 v23, v22, v7
	v_fma_f32 v24, -v0, v23, v22
	v_fmac_f32_e32 v23, v24, v7
	v_fma_f32 v0, -v0, v23, v22
	v_div_fmas_f32 v0, v0, v7, v23
	v_div_fixup_f32 v13, v0, v13, v20
	v_div_scale_f32 v0, s[12:13], v12, v12, v21
	v_rcp_f32_e32 v7, v0
	s_nop 0
	v_fma_f32 v20, -v0, v7, 1.0
	v_fmac_f32_e32 v7, v20, v7
	v_div_scale_f32 v20, vcc, v21, v12, v21
	v_mul_f32_e32 v22, v20, v7
	v_fma_f32 v23, -v0, v22, v20
	v_fmac_f32_e32 v22, v23, v7
	v_fma_f32 v0, -v0, v22, v20
	v_div_fmas_f32 v0, v0, v7, v22
	v_div_fixup_f32 v12, v0, v12, v21
	v_pk_mul_f32 v[12:13], v[12:13], v[18:19]
	v_and_b32_sdwa v0, v17, v179 dst_sel:DWORD dst_unused:UNUSED_PAD src0_sel:WORD_1 src1_sel:DWORD
	v_and_b32_sdwa v7, v16, v179 dst_sel:DWORD dst_unused:UNUSED_PAD src0_sel:WORD_1 src1_sel:DWORD
	v_add3_u32 v7, v16, v7, s14
	v_add3_u32 v0, v17, v0, s14
	v_and_b32_sdwa v16, v13, v179 dst_sel:DWORD dst_unused:UNUSED_PAD src0_sel:WORD_1 src1_sel:DWORD
	v_and_b32_sdwa v17, v12, v179 dst_sel:DWORD dst_unused:UNUSED_PAD src0_sel:WORD_1 src1_sel:DWORD
	v_add3_u32 v13, v13, v16, s14
	v_add3_u32 v12, v12, v17, s14
	v_and_b32_e32 v13, 0xffff0000, v13
	v_and_b32_e32 v12, 0xffff0000, v12
	v_add_co_u32_e32 v14, vcc, s6, v14
	v_or_b32_sdwa v13, v13, v0 dst_sel:DWORD dst_unused:UNUSED_PAD src0_sel:DWORD src1_sel:WORD_1
	v_or_b32_sdwa v12, v12, v7 dst_sel:DWORD dst_unused:UNUSED_PAD src0_sel:DWORD src1_sel:WORD_1
	v_addc_co_u32_e32 v15, vcc, 0, v15, vcc
	global_store_dwordx2 v[14:15], v[12:13], off offset:2048
	global_load_dwordx2 v[12:13], v[10:11], off offset:32
	v_mov_b32_e32 v16, v32
	v_mov_b32_e32 v17, v30
	v_mov_b32_e32 v30, v33
	s_waitcnt vmcnt(0)
; __device__ __forceinline__ unsigned pk2(float lo, float hi) { return f2bf(lo) | (f2bf(hi) << 16); }
; __device__ __forceinline__ float bflo(unsigned u) { return __uint_as_float(u << 16); }
; __device__ __forceinline__ float bfhi(unsigned u) { return __uint_as_float(u & 0xffff0000u); }
; __device__ __forceinline__ float silu_f(float v) { return v / (1.f + __expf(-v)); }
; __device__ __forceinline__ void ret2_task(const Params& p_, int l, int task, unsigned char* lds) {
;     ...
;     for (int et = 0; et < 4; ++et) { const u32x2 gz = *(const u32x2*)(Z + tok * DIN + 9 * DG + h * 64 + 16 * et + 4 * fq); u32x2 o;
;         o.x = pk2(tot[et][0] * rs * silu_f(bflo(gz.x)), tot[et][1] * rs * silu_f(bfhi(gz.x))); o.y = pk2(tot[et][2] * rs * silu_f(bflo(gz.y)), tot[et][3] * rs * silu_f(bfhi(gz.y)));
;         *(u32x2*)(CAT + tok * DM + 1024 + h * 64 + 16 * et + 4 * fq) = o; }
	v_lshlrev_b32_e32 v0, 16, v13
	v_lshlrev_b32_e32 v7, 16, v12
	v_mul_f32_e32 v14, 0xbfb8aa3b, v7
	v_and_b32_e32 v18, 0xffff0000, v13
	v_mul_f32_e32 v13, 0xbfb8aa3b, v0
	v_exp_f32_e32 v14, v14
	v_exp_f32_e32 v15, v13
	v_and_b32_e32 v19, 0xffff0000, v12
	v_mul_f32_e32 v12, 0xbfb8aa3b, v19
	v_exp_f32_e32 v12, v12
	v_pk_add_f32 v[14:15], v[14:15], 1.0 op_sel_hi:[1,0]
	v_pk_mul_f32 v[16:17], v[16:17], v[6:7] op_sel_hi:[1,0]
	v_div_scale_f32 v13, s[12:13], v15, v15, v0
	v_rcp_f32_e32 v20, v13
	s_nop 0
	v_fma_f32 v21, -v13, v20, 1.0
	v_fmac_f32_e32 v20, v21, v20
	v_div_scale_f32 v21, vcc, v0, v15, v0
	v_mul_f32_e32 v22, v21, v20
	v_fma_f32 v23, -v13, v22, v21
	v_fmac_f32_e32 v22, v23, v20
	v_fma_f32 v13, -v13, v22, v21
	v_div_fmas_f32 v13, v13, v20, v22
	v_div_fixup_f32 v15, v13, v15, v0
	v_div_scale_f32 v0, s[12:13], v14, v14, v7
	v_rcp_f32_e32 v13, v0
	s_nop 0
	v_fma_f32 v20, -v0, v13, 1.0
	v_fmac_f32_e32 v13, v20, v13
	v_div_scale_f32 v20, vcc, v7, v14, v7
	v_mul_f32_e32 v21, v20, v13
	v_fma_f32 v22, -v0, v21, v20
	v_fmac_f32_e32 v21, v22, v13
	v_fma_f32 v0, -v0, v21, v20
	v_div_fmas_f32 v0, v0, v13, v21
	v_div_fixup_f32 v14, v0, v14, v7
	v_mul_f32_e32 v0, 0xbfb8aa3b, v18
	v_exp_f32_e32 v13, v0
	v_pk_mul_f32 v[14:15], v[14:15], v[16:17]
	v_pk_mul_f32 v[16:17], v[30:31], v[6:7] op_sel_hi:[1,0]
	v_pk_add_f32 v[12:13], v[12:13], 1.0 op_sel_hi:[1,0]
	s_nop 0
	v_div_scale_f32 v0, s[12:13], v13, v13, v18
	v_rcp_f32_e32 v7, v0
	s_nop 0
	v_fma_f32 v20, -v0, v7, 1.0
	v_fmac_f32_e32 v7, v20, v7
	v_div_scale_f32 v20, vcc, v18, v13, v18
	v_mul_f32_e32 v21, v20, v7
	v_fma_f32 v22, -v0, v21, v20
	v_fmac_f32_e32 v21, v22, v7
	v_fma_f32 v0, -v0, v21, v20
	v_div_fmas_f32 v0, v0, v7, v21
	v_div_fixup_f32 v13, v0, v13, v18
	v_div_scale_f32 v0, s[12:13], v12, v12, v19
	v_rcp_f32_e32 v7, v0
	s_nop 0
	v_fma_f32 v18, -v0, v7, 1.0
	v_fmac_f32_e32 v7, v18, v7
	v_div_scale_f32 v18, vcc, v19, v12, v19
	v_mul_f32_e32 v20, v18, v7
	v_fma_f32 v21, -v0, v20, v18
	v_fmac_f32_e32 v20, v21, v7
	v_fma_f32 v0, -v0, v20, v18
	v_div_fmas_f32 v0, v0, v7, v20
	v_div_fixup_f32 v12, v0, v12, v19
	v_pk_mul_f32 v[12:13], v[12:13], v[16:17]
	v_and_b32_sdwa v0, v15, v179 dst_sel:DWORD dst_unused:UNUSED_PAD src0_sel:WORD_1 src1_sel:DWORD
	v_and_b32_sdwa v7, v14, v179 dst_sel:DWORD dst_unused:UNUSED_PAD src0_sel:WORD_1 src1_sel:DWORD
	v_add3_u32 v7, v14, v7, s14
	v_add3_u32 v0, v15, v0, s14
	v_and_b32_sdwa v14, v13, v179 dst_sel:DWORD dst_unused:UNUSED_PAD src0_sel:WORD_1 src1_sel:DWORD
	v_and_b32_sdwa v15, v12, v179 dst_sel:DWORD dst_unused:UNUSED_PAD src0_sel:WORD_1 src1_sel:DWORD
	v_add3_u32 v13, v13, v14, s14
	v_add3_u32 v12, v12, v15, s14
	v_and_b32_e32 v13, 0xffff0000, v13
	v_and_b32_e32 v12, 0xffff0000, v12
	v_or_b32_sdwa v13, v13, v0 dst_sel:DWORD dst_unused:UNUSED_PAD src0_sel:DWORD src1_sel:WORD_1
	v_or_b32_sdwa v12, v12, v7 dst_sel:DWORD dst_unused:UNUSED_PAD src0_sel:DWORD src1_sel:WORD_1
	global_store_dwordx2 v[8:9], v[12:13], off offset:32
	global_load_dwordx2 v[12:13], v[10:11], off offset:64
	v_mov_b32_e32 v16, v28
	global_load_dwordx2 v[10:11], v[10:11], off offset:96
	v_mov_b32_e32 v17, v26
	v_mov_b32_e32 v26, v29
	s_waitcnt vmcnt(1)
; __device__ __forceinline__ unsigned pk2(float lo, float hi) { return f2bf(lo) | (f2bf(hi) << 16); }
; __device__ __forceinline__ float bflo(unsigned u) { return __uint_as_float(u << 16); }
; __device__ __forceinline__ float bfhi(unsigned u) { return __uint_as_float(u & 0xffff0000u); }
; __device__ __forceinline__ float silu_f(float v) { return v / (1.f + __expf(-v)); }
; __device__ __forceinline__ void ret2_task(const Params& p_, int l, int task, unsigned char* lds) {
;     ...
;     for (int et = 0; et < 4; ++et) { const u32x2 gz = *(const u32x2*)(Z + tok * DIN + 9 * DG + h * 64 + 16 * et + 4 * fq); u32x2 o;
;         o.x = pk2(tot[et][0] * rs * silu_f(bflo(gz.x)), tot[et][1] * rs * silu_f(bfhi(gz.x))); o.y = pk2(tot[et][2] * rs * silu_f(bflo(gz.y)), tot[et][3] * rs * silu_f(bfhi(gz.y)));
;         *(u32x2*)(CAT + tok * DM + 1024 + h * 64 + 16 * et + 4 * fq) = o; }
;     __syncthreads();
	v_lshlrev_b32_e32 v0, 16, v13
	v_lshlrev_b32_e32 v7, 16, v12
	v_mul_f32_e32 v14, 0xbfb8aa3b, v7
	v_and_b32_e32 v18, 0xffff0000, v13
	v_mul_f32_e32 v13, 0xbfb8aa3b, v0
	v_exp_f32_e32 v14, v14
	v_exp_f32_e32 v15, v13
	v_and_b32_e32 v19, 0xffff0000, v12
	v_mul_f32_e32 v12, 0xbfb8aa3b, v19
	v_exp_f32_e32 v12, v12
	v_pk_add_f32 v[14:15], v[14:15], 1.0 op_sel_hi:[1,0]
	v_pk_mul_f32 v[16:17], v[16:17], v[6:7] op_sel_hi:[1,0]
	v_div_scale_f32 v13, s[12:13], v15, v15, v0
	v_rcp_f32_e32 v20, v13
	s_nop 0
	v_fma_f32 v21, -v13, v20, 1.0
	v_fmac_f32_e32 v20, v21, v20
	v_div_scale_f32 v21, vcc, v0, v15, v0
	v_mul_f32_e32 v22, v21, v20
	v_fma_f32 v23, -v13, v22, v21
	v_fmac_f32_e32 v22, v23, v20
	v_fma_f32 v13, -v13, v22, v21
	v_div_fmas_f32 v13, v13, v20, v22
	v_div_fixup_f32 v15, v13, v15, v0
	v_div_scale_f32 v0, s[12:13], v14, v14, v7
	v_rcp_f32_e32 v13, v0
	s_nop 0
	v_fma_f32 v20, -v0, v13, 1.0
	v_fmac_f32_e32 v13, v20, v13
	v_div_scale_f32 v20, vcc, v7, v14, v7
	v_mul_f32_e32 v21, v20, v13
	v_fma_f32 v22, -v0, v21, v20
	v_fmac_f32_e32 v21, v22, v13
	v_fma_f32 v0, -v0, v21, v20
	v_div_fmas_f32 v0, v0, v13, v21
	v_div_fixup_f32 v14, v0, v14, v7
	v_mul_f32_e32 v0, 0xbfb8aa3b, v18
	v_exp_f32_e32 v13, v0
	v_pk_mul_f32 v[14:15], v[14:15], v[16:17]
	v_pk_mul_f32 v[16:17], v[26:27], v[6:7] op_sel_hi:[1,0]
	v_pk_add_f32 v[12:13], v[12:13], 1.0 op_sel_hi:[1,0]
	s_nop 0
	v_div_scale_f32 v0, s[12:13], v13, v13, v18
	v_rcp_f32_e32 v7, v0
	s_nop 0
	v_fma_f32 v20, -v0, v7, 1.0
	v_fmac_f32_e32 v7, v20, v7
	v_div_scale_f32 v20, vcc, v18, v13, v18
	v_mul_f32_e32 v21, v20, v7
	v_fma_f32 v22, -v0, v21, v20
	v_fmac_f32_e32 v21, v22, v7
	v_fma_f32 v0, -v0, v21, v20
	v_div_fmas_f32 v0, v0, v7, v21
	v_div_fixup_f32 v13, v0, v13, v18
	v_div_scale_f32 v0, s[12:13], v12, v12, v19
	v_rcp_f32_e32 v7, v0
	s_nop 0
	v_fma_f32 v18, -v0, v7, 1.0
	v_fmac_f32_e32 v7, v18, v7
	v_div_scale_f32 v18, vcc, v19, v12, v19
	v_mul_f32_e32 v20, v18, v7
	v_fma_f32 v21, -v0, v20, v18
	v_fmac_f32_e32 v20, v21, v7
	v_fma_f32 v0, -v0, v20, v18
	v_div_fmas_f32 v0, v0, v7, v20
	v_div_fixup_f32 v12, v0, v12, v19
	v_pk_mul_f32 v[12:13], v[12:13], v[16:17]
	v_and_b32_sdwa v0, v15, v179 dst_sel:DWORD dst_unused:UNUSED_PAD src0_sel:WORD_1 src1_sel:DWORD
	v_and_b32_sdwa v7, v14, v179 dst_sel:DWORD dst_unused:UNUSED_PAD src0_sel:WORD_1 src1_sel:DWORD
	v_add3_u32 v7, v14, v7, s14
	v_add3_u32 v0, v15, v0, s14
	v_and_b32_sdwa v14, v13, v179 dst_sel:DWORD dst_unused:UNUSED_PAD src0_sel:WORD_1 src1_sel:DWORD
	v_and_b32_sdwa v15, v12, v179 dst_sel:DWORD dst_unused:UNUSED_PAD src0_sel:WORD_1 src1_sel:DWORD
	v_add3_u32 v13, v13, v14, s14
	v_add3_u32 v12, v12, v15, s14
	v_and_b32_e32 v13, 0xffff0000, v13
	v_and_b32_e32 v12, 0xffff0000, v12
	v_or_b32_sdwa v13, v13, v0 dst_sel:DWORD dst_unused:UNUSED_PAD src0_sel:DWORD src1_sel:WORD_1
	v_or_b32_sdwa v12, v12, v7 dst_sel:DWORD dst_unused:UNUSED_PAD src0_sel:DWORD src1_sel:WORD_1
	s_waitcnt vmcnt(0)
	v_lshlrev_b32_e32 v0, 16, v11
	v_lshlrev_b32_e32 v7, 16, v10
	global_store_dwordx2 v[8:9], v[12:13], off offset:64
	v_mul_f32_e32 v12, 0xbfb8aa3b, v7
	v_mov_b32_e32 v15, v2
	v_mul_f32_e32 v2, 0xbfb8aa3b, v0
	v_exp_f32_e32 v12, v12
	v_exp_f32_e32 v13, v2
	v_mov_b32_e32 v14, v4
	v_and_b32_e32 v16, 0xffff0000, v11
	v_and_b32_e32 v17, 0xffff0000, v10
	v_pk_add_f32 v[12:13], v[12:13], 1.0 op_sel_hi:[1,0]
	v_mul_f32_e32 v10, 0xbfb8aa3b, v17
	v_div_scale_f32 v2, s[12:13], v13, v13, v0
	v_rcp_f32_e32 v4, v2
	v_exp_f32_e32 v10, v10
	v_pk_mul_f32 v[14:15], v[14:15], v[6:7] op_sel_hi:[1,0]
	v_fma_f32 v11, -v2, v4, 1.0
	v_fmac_f32_e32 v4, v11, v4
	v_div_scale_f32 v11, vcc, v0, v13, v0
	v_mul_f32_e32 v18, v11, v4
	v_fma_f32 v19, -v2, v18, v11
	v_fmac_f32_e32 v18, v19, v4
	v_fma_f32 v2, -v2, v18, v11
	v_div_fmas_f32 v2, v2, v4, v18
	v_div_fixup_f32 v13, v2, v13, v0
	v_div_scale_f32 v0, s[12:13], v12, v12, v7
	v_rcp_f32_e32 v2, v0
	s_nop 0
	v_fma_f32 v4, -v0, v2, 1.0
	v_fmac_f32_e32 v2, v4, v2
	v_div_scale_f32 v4, vcc, v7, v12, v7
	v_mul_f32_e32 v11, v4, v2
	v_fma_f32 v18, -v0, v11, v4
	v_fmac_f32_e32 v11, v18, v2
	v_fma_f32 v0, -v0, v11, v4
	v_div_fmas_f32 v0, v0, v2, v11
	v_div_fixup_f32 v12, v0, v12, v7
	v_mul_f32_e32 v0, 0xbfb8aa3b, v16
	v_exp_f32_e32 v11, v0
	v_mov_b32_e32 v2, v5
	v_pk_mul_f32 v[2:3], v[2:3], v[6:7] op_sel_hi:[1,0]
	v_pk_mul_f32 v[12:13], v[14:15], v[12:13]
	v_pk_add_f32 v[4:5], v[10:11], 1.0 op_sel_hi:[1,0]
	s_nop 0
	v_div_scale_f32 v0, s[12:13], v5, v5, v16
	v_rcp_f32_e32 v6, v0
	s_nop 0
	v_fma_f32 v7, -v0, v6, 1.0
	v_fmac_f32_e32 v6, v7, v6
	v_div_scale_f32 v7, vcc, v16, v5, v16
	v_mul_f32_e32 v10, v7, v6
	v_fma_f32 v11, -v0, v10, v7
	v_fmac_f32_e32 v10, v11, v6
	v_fma_f32 v0, -v0, v10, v7
	v_div_fmas_f32 v0, v0, v6, v10
	v_div_fixup_f32 v5, v0, v5, v16
	v_div_scale_f32 v0, s[12:13], v4, v4, v17
	v_rcp_f32_e32 v6, v0
	s_nop 0
	v_fma_f32 v7, -v0, v6, 1.0
	v_fmac_f32_e32 v6, v7, v6
	v_div_scale_f32 v7, vcc, v17, v4, v17
	v_mul_f32_e32 v10, v7, v6
	v_fma_f32 v11, -v0, v10, v7
	v_fmac_f32_e32 v10, v11, v6
	v_fma_f32 v0, -v0, v10, v7
	v_div_fmas_f32 v0, v0, v6, v10
	v_div_fixup_f32 v4, v0, v4, v17
	v_pk_mul_f32 v[2:3], v[2:3], v[4:5]
	v_and_b32_sdwa v0, v13, v179 dst_sel:DWORD dst_unused:UNUSED_PAD src0_sel:WORD_1 src1_sel:DWORD
	v_and_b32_sdwa v5, v3, v179 dst_sel:DWORD dst_unused:UNUSED_PAD src0_sel:WORD_1 src1_sel:DWORD
	v_and_b32_sdwa v6, v2, v179 dst_sel:DWORD dst_unused:UNUSED_PAD src0_sel:WORD_1 src1_sel:DWORD
	v_and_b32_sdwa v4, v12, v179 dst_sel:DWORD dst_unused:UNUSED_PAD src0_sel:WORD_1 src1_sel:DWORD
	v_add3_u32 v3, v3, v5, s14
	v_add3_u32 v2, v2, v6, s14
	v_add3_u32 v4, v12, v4, s14
	v_add3_u32 v0, v13, v0, s14
	v_and_b32_e32 v3, 0xffff0000, v3
	v_and_b32_e32 v2, 0xffff0000, v2
	v_or_b32_sdwa v3, v3, v0 dst_sel:DWORD dst_unused:UNUSED_PAD src0_sel:DWORD src1_sel:WORD_1
	v_or_b32_sdwa v2, v2, v4 dst_sel:DWORD dst_unused:UNUSED_PAD src0_sel:DWORD src1_sel:WORD_1
	global_store_dwordx2 v[8:9], v[2:3], off offset:96
	s_barrier
	s_cbranch_scc0 .LBB0_577
